# two-level pair barrier where the first arriver of each XCD also starts an early L2 write-back (final write-back by the last arriver has less to do)
# baseline (speedup 1.0000x reference)
; __device__ __forceinline__ unsigned xb_ld(unsigned* p)              { return __hip_atomic_load(p, __ATOMIC_RELAXED, __HIP_MEMORY_SCOPE_AGENT); }
; __device__ __forceinline__ unsigned xb_add(unsigned* p, unsigned v) { return __hip_atomic_fetch_add(p, v, __ATOMIC_RELAXED, __HIP_MEMORY_SCOPE_AGENT); }
; #define XB_SPIN(cond, bar) do { unsigned _sp = 0; while (cond) { __builtin_amdgcn_s_sleep(1); \
;     if ((++_sp & 255u) == 0u) { if (xb_ld(&(bar)[XB_TMO])) break; if (_sp > XB_SPIN_CAP) { atomicAdd(&(bar)[XB_TMO], 1u); break; } } } } while (0)
; __device__ __forceinline__ void xcd_barrier(const XcdBarrier& b) {
;     asm volatile("s_waitcnt vmcnt(0)" ::: "memory");
;     __syncthreads();
;     if (threadIdx.x == 0) {
;         unsigned* bar = b.bar;
;         __builtin_amdgcn_s_waitcnt(0);
;         unsigned nloc = b.st[0], nx = b.st[1];
;         if (nloc == 0u) { xcd_barrier_complete(bar, b.x, nloc, nx); b.st[0] = nloc; b.st[1] = nx; }
;         const unsigned old = xb_add(&bar[XB_XSUB(b.x)], 1u);
;         const unsigned gen = old / nloc;
;         if (old + 1u == (gen + 1u) * nloc) {
;             __builtin_amdgcn_fence(__ATOMIC_RELEASE, "agent");
;             asm volatile("s_waitcnt vmcnt(0)" ::: "memory");
;             const unsigned og = xb_add(&bar[XB_TOP], 1u);
;             const unsigned tg = og / nx;
;             if (og + 1u == (tg + 1u) * nx) xb_add(&bar[XB_TOPGEN], 1u);
;             else XB_SPIN(xb_ld(&bar[XB_TOPGEN]) == tg, bar);
;             __builtin_amdgcn_fence(__ATOMIC_ACQUIRE, "agent");
;             xb_add(&bar[XB_XGEN(b.x)], 1u);
;             asm volatile("s_waitcnt vmcnt(0)" ::: "memory");
;         } else {
;             XB_SPIN(xb_ld(&bar[XB_XGEN(b.x)]) == gen, bar);
;             __builtin_amdgcn_fence(__ATOMIC_ACQUIRE, "agent");
;             asm volatile("s_waitcnt vmcnt(0)" ::: "memory");
;         }
;     }
;     __syncthreads();
; }
.LBB0_192:
	s_waitcnt vmcnt(0)
	s_waitcnt vmcnt(0) lgkmcnt(0)
	s_barrier
	s_mov_b64 s[2:3], exec
	v_readlane_b32 s12, v253, 36
	v_readlane_b32 s13, v253, 37
	s_and_b64 s[12:13], s[2:3], s[12:13]
	s_mov_b64 exec, s[12:13]
	s_cbranch_execz .LBB0_244
	s_cmp_lg_u32 s98, 0
	s_cbranch_scc0 .Lgb_full_244
	v_readlane_b32 s4, v253, 1
	v_readlane_b32 s12, v253, 56
	v_readlane_b32 s13, v253, 57
	s_nop 3
	s_and_b32 s17, s4, 7
	s_lshl_b32 s17, s17, 6
	s_add_i32 s17, s17, 0x7400
	v_mov_b32_e32 v4, s17
	s_bfe_u32 s4, s4, 0x20001
	s_lshl_b32 s4, s4, 8
	s_add_i32 s4, s4, 0x7000
	v_mov_b32_e32 v2, s4
	s_add_i32 s16, s92, 1
	s_lshl_b32 s17, s16, 5
	s_lshl_b32 s16, s16, 1
	s_mov_b32 s1, 0
	s_nop 1
	global_atomic_add v5, v4, v234, s[12:13] sc0
	s_waitcnt vmcnt(0)
	v_readfirstlane_b32 s4, v5
	s_nop 3
	s_add_i32 s4, s4, 1
	s_sub_i32 s18, s17, 31
	s_cmp_lg_u32 s4, s18
	s_cbranch_scc1 .Lgb_pair_nf_244
	buffer_wbl2 sc1
.Lgb_pair_nf_244:
	s_cmp_lg_u32 s4, s17
	s_cbranch_scc1 .Lgb_pair_244
	buffer_wbl2 sc1
	s_waitcnt vmcnt(0)
	global_atomic_add v2, v234, s[12:13]
	s_waitcnt vmcnt(0)
